# attention K-loops: remaining scalar output-rescale multiplies packed into v_pk_mul_f32 and the two 0+x adds at the head of the row-sum chains folded away (6 fewer VALU issues per tile)
# baseline (speedup 1.0000x reference)
; DI void attn_task(const Params& P, int set, int b, int kvh, int qt, char* smem) {
;     ...
;   for (int kt = 0; kt < ntile; ++kt) {
;     if (kt + 1 < ntile) {
;       kreg = *(const half8*)(kg + (size_t)((kt + 1) * 64 + srow) * 64 + sch * 8);
;       vreg = *(const half8*)(vg + (size_t)srow * SKV + (kt + 1) * 64 + sch * 8);
;     }
;     const char* s = smem + (kt & 1) * 16384;
;     ...
;       float ps = 0.f;
; #pragma unroll
;       for (int v = 0; v < 16; ++v) {
;         sc[qi][0][v] = __builtin_amdgcn_exp2f(sc[qi][0][v] * cscale - m_new); ps += sc[qi][0][v];
;         sc[qi][1][v] = __builtin_amdgcn_exp2f(sc[qi][1][v] * cscale - m_new); ps += sc[qi][1][v];
;       }
;       l_run[qi] = l_run[qi] * alpha + ps;
; #pragma unroll
;       for (int v = 0; v < 16; ++v) { o[qi][0][v] *= alpha; o[qi][1][v] *= alpha; }
.LBB0_74:
	v_add_f32_e32 v91, v190, v189
	v_add_f32_e32 v80, v80, v119
	v_add_f32_e32 v91, v191, v91
	v_add_f32_e32 v80, v120, v80
	v_add_f32_e32 v91, v192, v91
	v_add_f32_e32 v80, v87, v80
	v_add_f32_e32 v91, v193, v91
	v_add_f32_e32 v80, v121, v80
	v_add_f32_e32 v91, v194, v91
	v_add_f32_e32 v80, v81, v80
	v_add_f32_e32 v91, v195, v91
	v_add_f32_e32 v80, v122, v80
	v_add_f32_e32 v91, v196, v91
	v_add_f32_e32 v80, v86, v80
	v_add_f32_e32 v91, v197, v91
	v_add_f32_e32 v80, v100, v80
	v_add_f32_e32 v91, v198, v91
	v_add_f32_e32 v80, v84, v80
	v_add_f32_e32 v91, v199, v91
	v_add_f32_e32 v80, v101, v80
	v_add_f32_e32 v91, v200, v91
	v_add_f32_e32 v80, v85, v80
	v_add_f32_e32 v91, v201, v91
	v_add_f32_e32 v80, v102, v80
	v_add_f32_e32 v91, v202, v91
	v_add_f32_e32 v80, v82, v80
	v_add_f32_e32 v91, v203, v91
	v_add_f32_e32 v80, v103, v80
	v_add_f32_e32 v91, v204, v91
	v_add_f32_e32 v80, v83, v80
	v_add_f32_e32 v91, v116, v91
	v_add_f32_e32 v80, v104, v80
	v_add_f32_e32 v91, v205, v91
	v_add_f32_e32 v80, v88, v80
	v_add_f32_e32 v91, v117, v91
	v_add_f32_e32 v80, v106, v80
	v_add_f32_e32 v91, v206, v91
	v_add_f32_e32 v80, v90, v80
	v_add_f32_e32 v91, v118, v91
	v_add_f32_e32 v80, v105, v80
	v_add_f32_e32 v91, v207, v91
	v_add_f32_e32 v90, v89, v80
	v_pk_add_f32 v[80:81], v[112:113], v[90:91]
	v_mov_b32_e32 v97, v114
	v_pk_add_f32 v[72:73], v[72:73], v[80:81]
	s_add_i32 s43, s43, 1
	v_pk_add_f32 v[70:71], v[70:71], v[72:73]
	s_mov_b64 s[2:3], 0x2000
	v_pk_add_f32 v[68:69], v[68:69], v[70:71]
	v_lshl_add_u64 v[176:177], v[176:177], 0, s[2:3]
	v_pk_add_f32 v[66:67], v[66:67], v[68:69]
	v_lshl_add_u64 v[178:179], v[178:179], 0, s[22:23]
	v_pk_add_f32 v[64:65], v[64:65], v[66:67]
	s_cmp_lg_u32 s43, 4
	v_pk_add_f32 v[64:65], v[76:77], v[64:65]
	s_mov_b32 s44, s24
	v_pk_add_f32 v[64:65], v[98:99], v[64:65]
	v_mov_b32_e32 v224, v115
	v_pk_add_f32 v[64:65], v[74:75], v[64:65]
	v_mov_b32_e32 v80, v128
	v_pk_add_f32 v[64:65], v[78:79], v[64:65]
	s_waitcnt lgkmcnt(0)
	v_pk_fma_f32 v[168:169], v[168:169], v[96:97], v[64:65]
	s_barrier
	s_cbranch_scc0 .LBB0_81

; DI void attn_task(const Params& P, int set, int b, int kvh, int qt, char* smem) {
;     ...
;     const char* s = smem + (kt & 1) * 16384;
;     f32x16 sc[2][2];
; #pragma unroll
;     for (int qi = 0; qi < 2; ++qi)
; #pragma unroll
;       for (int v = 0; v < 16; ++v) { sc[qi][0][v] = 0.f; sc[qi][1][v] = 0.f; }
; #pragma unroll
;     for (int ds = 0; ds < 4; ++ds) {
;       const int co = ((2 * ds + hh) ^ sw) * 16;
;       const half8 k0 = *(const half8*)(s + r32 * 128 + co);
;       const half8 k1 = *(const half8*)(s + (32 + r32) * 128 + co);
; #pragma unroll
;       for (int qi = 0; qi < 2; ++qi) {
;         sc[qi][0] = __builtin_amdgcn_mfma_f32_32x32x16_f16(k0, qf[qi][ds], sc[qi][0], 0, 0, 0);
;         sc[qi][1] = __builtin_amdgcn_mfma_f32_32x32x16_f16(k1, qf[qi][ds], sc[qi][1], 0, 0, 0);
;       }
;     }
; #pragma unroll
;     for (int qi = 0; qi < 2; ++qi) {
;       float mx = sc[qi][0][0];
; #pragma unroll
;       for (int v = 0; v < 16; ++v) { mx = fmaxf(mx, sc[qi][0][v]); mx = fmaxf(mx, sc[qi][1][v]); }
;       mx = fmaxf(mx, __shfl_xor(mx, 32));
;       const float m_new = fmaxf(m_run[qi], mx * cscale);
;       const float alpha = __builtin_amdgcn_exp2f(m_run[qi] - m_new);
;       m_run[qi] = m_new;
;       float ps = 0.f;
; #pragma unroll
;       for (int v = 0; v < 16; ++v) {
;         sc[qi][0][v] = __builtin_amdgcn_exp2f(sc[qi][0][v] * cscale - m_new); ps += sc[qi][0][v];
;         sc[qi][1][v] = __builtin_amdgcn_exp2f(sc[qi][1][v] * cscale - m_new); ps += sc[qi][1][v];
;       }
.LBB0_77:
	s_and_b32 s2, s44, 0x4000
	v_add_u32_e32 v81, s2, v188
	v_add_u32_e32 v216, v81, v184
	ds_read_b128 v[82:85], v216
	ds_read_b128 v[86:89], v216 offset:4096
	v_add_u32_e32 v217, v81, v185
	ds_read_b128 v[200:203], v217
	ds_read_b128 v[204:207], v217 offset:4096
	v_add_u32_e32 v220, v81, v186
	s_waitcnt lgkmcnt(3)
	v_mfma_f32_32x32x16_f16 v[108:123], v[82:85], v[162:165], 0
	ds_read_b128 v[210:213], v220
	ds_read_b128 v[226:229], v220 offset:4096
	v_add_u32_e32 v223, v81, v187
	ds_read_b128 v[230:233], v223 offset:4096
	ds_read_b128 v[234:237], v223
	v_max_f32_e32 v91, v80, v80
	s_andn2_b64 vcc, exec, s[38:39]
	s_mov_b64 s[2:3], -1
	s_waitcnt lgkmcnt(6)
	v_mfma_f32_32x32x16_f16 v[64:79], v[86:89], v[162:165], 0
	s_waitcnt lgkmcnt(5)
	v_mfma_f32_32x32x16_f16 v[108:123], v[200:203], v[158:161], v[108:123]
	s_waitcnt lgkmcnt(4)
	v_mfma_f32_32x32x16_f16 v[64:79], v[204:207], v[158:161], v[64:79]
	s_waitcnt lgkmcnt(3)
	v_mfma_f32_32x32x16_f16 v[108:123], v[210:213], v[154:157], v[108:123]
	s_waitcnt lgkmcnt(2)
	v_mfma_f32_32x32x16_f16 v[64:79], v[226:229], v[154:157], v[64:79]
	s_waitcnt lgkmcnt(1)
	v_mfma_f32_32x32x16_f16 v[64:79], v[230:233], v[150:153], v[64:79]
	s_waitcnt lgkmcnt(0)
	v_mfma_f32_32x32x16_f16 v[108:123], v[234:237], v[150:153], v[108:123]
	s_nop 9
	v_max_f32_e32 v81, v64, v64
	s_nop 0
	v_max_f32_e32 v90, v108, v108
	v_max_f32_e32 v81, v90, v81
	v_max3_f32 v81, v81, v109, v65
	v_max3_f32 v81, v81, v110, v66
	v_max3_f32 v81, v81, v111, v67
	v_max3_f32 v81, v81, v112, v68
	v_max3_f32 v81, v81, v113, v69
	v_max3_f32 v81, v81, v114, v70
	v_max3_f32 v81, v81, v115, v71
	v_max3_f32 v81, v81, v116, v72
	v_max3_f32 v81, v81, v117, v73
	v_max3_f32 v81, v81, v118, v74
	v_max3_f32 v81, v81, v119, v75
	v_max3_f32 v81, v81, v120, v76
	v_max3_f32 v81, v81, v121, v77
	v_max3_f32 v81, v81, v122, v78
	v_max3_f32 v81, v81, v123, v79
	ds_bpermute_b32 v90, v175, v81
	s_waitcnt lgkmcnt(0)
	v_max_f32_e32 v90, v90, v90
	v_max_f32_e32 v81, v81, v90
	v_mul_f32_e32 v81, 0x3e38aa3b, v81
	v_max_f32_e32 v128, v91, v81
	v_sub_f32_e32 v221, v80, v128
	v_fma_f32 v80, v108, s28, -v128
	v_fma_f32 v81, v109, s28, -v128
	v_fma_f32 v90, v110, s28, -v128
	v_fma_f32 v91, v111, s28, -v128
	v_mfma_f32_32x32x16_f16 v[96:111], v[82:85], v[146:149], 0
	v_exp_f32_e32 v189, v80
	v_exp_f32_e32 v191, v81
	v_exp_f32_e32 v193, v90
	v_exp_f32_e32 v195, v91
	v_fma_f32 v64, v64, s28, -v128
	v_fma_f32 v66, v66, s28, -v128
	v_exp_f32_e32 v190, v64
	v_mfma_f32_32x32x16_f16 v[80:95], v[86:89], v[146:149], 0
	v_fma_f32 v64, v112, s28, -v128
	v_exp_f32_e32 v194, v66
	v_exp_f32_e32 v197, v64
	v_fma_f32 v64, v68, s28, -v128
	v_exp_f32_e32 v198, v64
	v_fma_f32 v64, v113, s28, -v128
	v_exp_f32_e32 v199, v64
	v_mfma_f32_32x32x16_f16 v[96:111], v[200:203], v[142:145], v[96:111]
	v_fma_f32 v64, v69, s28, -v128
	v_exp_f32_e32 v200, v64
	v_fma_f32 v64, v114, s28, -v128
	v_exp_f32_e32 v201, v64
	v_fma_f32 v64, v70, s28, -v128
	v_exp_f32_e32 v202, v64
	v_fma_f32 v64, v115, s28, -v128
	v_mfma_f32_32x32x16_f16 v[80:95], v[204:207], v[142:145], v[80:95]
	v_exp_f32_e32 v203, v64
	v_fma_f32 v64, v71, s28, -v128
	v_exp_f32_e32 v204, v64
	v_fma_f32 v64, v116, s28, -v128
	v_exp_f32_e32 v116, v64
	v_fma_f32 v64, v72, s28, -v128
	v_exp_f32_e32 v205, v64
	v_mfma_f32_32x32x16_f16 v[96:111], v[210:213], v[138:141], v[96:111]
	v_fma_f32 v64, v117, s28, -v128
	v_exp_f32_e32 v117, v64
	v_fma_f32 v64, v73, s28, -v128
	v_exp_f32_e32 v206, v64
	v_fma_f32 v64, v118, s28, -v128
	v_exp_f32_e32 v118, v64
	v_fma_f32 v64, v74, s28, -v128
	v_mfma_f32_32x32x16_f16 v[80:95], v[226:229], v[138:141], v[80:95]
	v_exp_f32_e32 v207, v64
	v_fma_f32 v64, v119, s28, -v128
	v_exp_f32_e32 v113, v64
	v_fma_f32 v64, v75, s28, -v128
	v_exp_f32_e32 v73, v64
	v_fma_f32 v64, v120, s28, -v128
	v_exp_f32_e32 v71, v64
	v_mfma_f32_32x32x16_f16 v[80:95], v[230:233], v[134:137], v[80:95]
	v_fma_f32 v64, v76, s28, -v128
	v_fma_f32 v67, v67, s28, -v128
	v_exp_f32_e32 v69, v64
	v_fma_f32 v64, v121, s28, -v128
	v_fma_f32 v65, v65, s28, -v128
	v_exp_f32_e32 v196, v67
	v_exp_f32_e32 v67, v64
	v_mfma_f32_32x32x16_f16 v[96:111], v[234:237], v[134:137], v[96:111]
	s_nop 3
	v_max_f32_e32 v66, v80, v80
	v_fma_f32 v64, v77, s28, -v128
	v_exp_f32_e32 v192, v65
	v_exp_f32_e32 v65, v64
	v_fma_f32 v64, v122, s28, -v128
	v_exp_f32_e32 v77, v64
	v_fma_f32 v64, v123, s28, -v128
	s_nop 0
	v_max_f32_e32 v68, v96, v96
	v_max_f32_e32 v66, v68, v66
	v_max3_f32 v66, v66, v97, v81
	v_max3_f32 v66, v66, v98, v82
	v_max3_f32 v66, v66, v99, v83
	v_max3_f32 v66, v66, v100, v84
	v_max3_f32 v66, v66, v101, v85
	v_max3_f32 v66, v66, v102, v86
	v_max3_f32 v66, v66, v103, v87
	v_max3_f32 v66, v66, v104, v88
	v_max3_f32 v66, v66, v105, v89
	v_max3_f32 v66, v66, v106, v90
	v_max3_f32 v66, v66, v107, v91
	v_max3_f32 v66, v66, v108, v92
	v_max3_f32 v66, v66, v109, v93
	v_max3_f32 v66, v66, v110, v94
	v_max3_f32 v66, v66, v111, v95
	ds_bpermute_b32 v68, v175, v66
	v_exp_f32_e32 v75, v64
	ds_read_b128 v[210:213], v216 offset:8192
	v_exp_f32_e32 v114, v221
	v_cvt_pk_f16_f32 v231, v201, v203
	s_waitcnt lgkmcnt(1)
; DI void attn_task(const Params& P, int set, int b, int kvh, int qt, char* smem) {
;     ...
;     for (int qi = 0; qi < 2; ++qi) {
;       float mx = sc[qi][0][0];
; #pragma unroll
;       for (int v = 0; v < 16; ++v) { mx = fmaxf(mx, sc[qi][0][v]); mx = fmaxf(mx, sc[qi][1][v]); }
;       mx = fmaxf(mx, __shfl_xor(mx, 32));
;       const float m_new = fmaxf(m_run[qi], mx * cscale);
;       const float alpha = __builtin_amdgcn_exp2f(m_run[qi] - m_new);
;       m_run[qi] = m_new;
;       float ps = 0.f;
; #pragma unroll
;       for (int v = 0; v < 16; ++v) {
;         sc[qi][0][v] = __builtin_amdgcn_exp2f(sc[qi][0][v] * cscale - m_new); ps += sc[qi][0][v];
;         sc[qi][1][v] = __builtin_amdgcn_exp2f(sc[qi][1][v] * cscale - m_new); ps += sc[qi][1][v];
;       }
;       l_run[qi] = l_run[qi] * alpha + ps;
; #pragma unroll
;       for (int v = 0; v < 16; ++v) { o[qi][0][v] *= alpha; o[qi][1][v] *= alpha; }
;     }
; #pragma unroll
;     for (int uu = 0; uu < 4; ++uu) {
;       const int co = ((2 * uu + hh) ^ sw) * 16;
;       const half8 v0 = *(const half8*)(s + 8192 + r32 * 128 + co);
;       const half8 v1 = *(const half8*)(s + 8192 + (32 + r32) * 128 + co);
; #pragma unroll
;       for (int qi = 0; qi < 2; ++qi) {
;         half8 pf;
; #pragma unroll
;         for (int j = 0; j < 8; ++j) pf[j] = (h16)((uu < 2) ? sc[qi][0][8 * (uu & 1) + j] : sc[qi][1][8 * (uu & 1) + j]);
;         o[qi][0] = __builtin_amdgcn_mfma_f32_32x32x16_f16(v0, pf, o[qi][0], 0, 0, 0);
;         o[qi][1] = __builtin_amdgcn_mfma_f32_32x32x16_f16(v1, pf, o[qi][1], 0, 0, 0);
;       }
;     }
	v_max_f32_e32 v64, v68, v68
	v_max_f32_e32 v64, v66, v64
	v_mul_f32_e32 v64, 0x3e38aa3b, v64
	v_max_f32_e32 v66, v224, v224
	v_max_f32_e32 v115, v66, v64
	v_fma_f32 v66, v96, s28, -v115
	v_exp_f32_e32 v119, v66
	v_fma_f32 v66, v97, s28, -v115
	v_exp_f32_e32 v120, v66
	v_fma_f32 v66, v98, s28, -v115
	v_sub_f32_e32 v64, v224, v115
	v_exp_f32_e32 v121, v66
	v_fma_f32 v66, v99, s28, -v115
	ds_read_b128 v[224:227], v216 offset:12288
	v_exp_f32_e32 v122, v66
	v_fma_f32 v66, v100, s28, -v115
	v_exp_f32_e32 v100, v66
	v_fma_f32 v66, v101, s28, -v115
	v_exp_f32_e32 v101, v66
	v_fma_f32 v66, v102, s28, -v115
	v_exp_f32_e32 v102, v66
	v_fma_f32 v66, v103, s28, -v115
	v_exp_f32_e32 v103, v66
	v_exp_f32_e32 v96, v64
	v_pk_mul_f32 v[62:63], v[62:63], v[114:115] op_sel_hi:[1,0]
	v_pk_mul_f32 v[60:61], v[60:61], v[114:115] op_sel_hi:[1,0]
	v_pk_mul_f32 v[58:59], v[58:59], v[114:115] op_sel_hi:[1,0]
	v_pk_mul_f32 v[56:57], v[56:57], v[114:115] op_sel_hi:[1,0]
	v_pk_mul_f32 v[54:55], v[54:55], v[114:115] op_sel_hi:[1,0]
	v_pk_mul_f32 v[52:53], v[52:53], v[114:115] op_sel_hi:[1,0]
	v_pk_mul_f32 v[50:51], v[50:51], v[114:115] op_sel_hi:[1,0]
	v_pk_mul_f32 v[48:49], v[48:49], v[114:115] op_sel_hi:[1,0]
	v_pk_mul_f32 v[46:47], v[46:47], v[114:115] op_sel_hi:[1,0]
	v_pk_mul_f32 v[44:45], v[44:45], v[114:115] op_sel_hi:[1,0]
	v_pk_mul_f32 v[42:43], v[42:43], v[114:115] op_sel_hi:[1,0]
	v_pk_mul_f32 v[40:41], v[40:41], v[114:115] op_sel_hi:[1,0]
	v_pk_mul_f32 v[38:39], v[38:39], v[114:115] op_sel_hi:[1,0]
	v_pk_mul_f32 v[36:37], v[36:37], v[114:115] op_sel_hi:[1,0]
	v_pk_mul_f32 v[34:35], v[34:35], v[114:115] op_sel_hi:[1,0]
	v_pk_mul_f32 v[32:33], v[32:33], v[114:115] op_sel_hi:[1,0]
	v_cvt_pk_f16_f32 v230, v197, v199
	v_cvt_pk_f16_f32 v229, v193, v195
	v_cvt_pk_f16_f32 v228, v189, v191
	v_pk_mul_f32 v[30:31], v[30:31], v[96:97] op_sel_hi:[1,0]
	v_pk_mul_f32 v[28:29], v[28:29], v[96:97] op_sel_hi:[1,0]
	s_waitcnt lgkmcnt(1)
	v_mfma_f32_32x32x16_f16 v[48:63], v[210:213], v[228:231], v[48:63]
	v_pk_mul_f32 v[26:27], v[26:27], v[96:97] op_sel_hi:[1,0]
	v_pk_mul_f32 v[24:25], v[24:25], v[96:97] op_sel_hi:[1,0]
	v_pk_mul_f32 v[22:23], v[22:23], v[96:97] op_sel_hi:[1,0]
	v_pk_mul_f32 v[20:21], v[20:21], v[96:97] op_sel_hi:[1,0]
	v_pk_mul_f32 v[18:19], v[18:19], v[96:97] op_sel_hi:[1,0]
	v_pk_mul_f32 v[16:17], v[16:17], v[96:97] op_sel_hi:[1,0]
	v_pk_mul_f32 v[14:15], v[14:15], v[96:97] op_sel_hi:[1,0]
	s_waitcnt lgkmcnt(0)
	v_mfma_f32_32x32x16_f16 v[32:47], v[224:227], v[228:231], v[32:47]
	v_pk_mul_f32 v[12:13], v[12:13], v[96:97] op_sel_hi:[1,0]
	v_cvt_pk_f16_f32 v231, v102, v103
	v_cvt_pk_f16_f32 v230, v100, v101
	v_cvt_pk_f16_f32 v229, v121, v122
	v_cvt_pk_f16_f32 v228, v119, v120
	v_pk_mul_f32 v[10:11], v[10:11], v[96:97] op_sel_hi:[1,0]
	v_pk_mul_f32 v[8:9], v[8:9], v[96:97] op_sel_hi:[1,0]
	v_pk_mul_f32 v[6:7], v[6:7], v[96:97] op_sel_hi:[1,0]
	v_pk_mul_f32 v[4:5], v[4:5], v[96:97] op_sel_hi:[1,0]
	v_pk_mul_f32 v[2:3], v[2:3], v[96:97] op_sel_hi:[1,0]
	v_pk_mul_f32 v[0:1], v[0:1], v[96:97] op_sel_hi:[1,0]
	v_fma_f32 v66, v104, s28, -v115
	v_mfma_f32_32x32x16_f16 v[16:31], v[210:213], v[228:231], v[16:31]
	ds_read_b128 v[210:213], v217 offset:8192
	v_exp_f32_e32 v104, v66
	v_fma_f32 v66, v106, s28, -v115
	v_fma_f32 v68, v105, s28, -v115
	v_exp_f32_e32 v105, v66
	v_fma_f32 v66, v108, s28, -v115
	v_fma_f32 v72, v110, s28, -v115
	v_mfma_f32_32x32x16_f16 v[0:15], v[224:227], v[228:231], v[0:15]
	ds_read_b128 v[224:227], v217 offset:12288
	v_fma_f32 v64, v107, s28, -v115
	v_exp_f32_e32 v70, v66
	v_fma_f32 v66, v109, s28, -v115
	v_exp_f32_e32 v76, v72
	v_fma_f32 v72, v111, s28, -v115
	v_exp_f32_e32 v74, v72
	v_exp_f32_e32 v66, v66
	v_exp_f32_e32 v112, v64
	v_exp_f32_e32 v106, v68
	v_cvt_pk_f16_f32 v231, v77, v75
	v_cvt_pk_f16_f32 v230, v71, v67
	v_cvt_pk_f16_f32 v229, v118, v113
	v_cvt_pk_f16_f32 v228, v116, v117
	v_cvt_pk_f16_f32 v111, v76, v74
	v_cvt_pk_f16_f32 v110, v70, v66
	v_cvt_pk_f16_f32 v109, v105, v112
	v_cvt_pk_f16_f32 v108, v104, v106
	s_waitcnt lgkmcnt(1)
	v_mfma_f32_32x32x16_f16 v[48:63], v[210:213], v[228:231], v[48:63]
	v_fma_f32 v64, v78, s28, -v128
	v_exp_f32_e32 v99, v64
	v_fma_f32 v64, v80, s28, -v115
	v_fma_f32 v68, v82, s28, -v115
	v_fma_f32 v72, v84, s28, -v115
	v_fma_f32 v78, v86, s28, -v115
	v_exp_f32_e32 v80, v64
	v_mfma_f32_32x32x16_f16 v[16:31], v[210:213], v[108:111], v[16:31]
	ds_read_b128 v[210:213], v220 offset:8192
	v_fma_f32 v64, v81, s28, -v115
	v_exp_f32_e32 v81, v68
	v_fma_f32 v68, v83, s28, -v115
	v_exp_f32_e32 v84, v72
	v_fma_f32 v72, v85, s28, -v115
	v_exp_f32_e32 v82, v78
	s_waitcnt lgkmcnt(1)
	v_mfma_f32_32x32x16_f16 v[0:15], v[224:227], v[108:111], v[0:15]
	ds_read_b128 v[108:111], v220 offset:12288
	v_fma_f32 v78, v87, s28, -v115
	v_exp_f32_e32 v83, v78
	v_exp_f32_e32 v85, v72
	v_exp_f32_e32 v86, v68
	v_exp_f32_e32 v87, v64
	v_fma_f32 v64, v79, s28, -v128
	v_mfma_f32_32x32x16_f16 v[32:47], v[224:227], v[228:231], v[32:47]
	v_cvt_pk_f16_f32 v227, v202, v204
	v_cvt_pk_f16_f32 v226, v198, v200
	v_cvt_pk_f16_f32 v225, v194, v196
	v_cvt_pk_f16_f32 v224, v190, v192
	v_exp_f32_e32 v79, v64
	v_fma_f32 v64, v88, s28, -v115
	v_exp_f32_e32 v88, v64
	s_waitcnt lgkmcnt(1)
	v_mfma_f32_32x32x16_f16 v[48:63], v[210:213], v[224:227], v[48:63]
	v_fma_f32 v64, v90, s28, -v115
	v_fma_f32 v97, v89, s28, -v115
	v_exp_f32_e32 v89, v64
	v_fma_f32 v64, v92, s28, -v115
	v_fma_f32 v78, v94, s28, -v115
	v_fma_f32 v72, v91, s28, -v115
	v_exp_f32_e32 v68, v64
	s_waitcnt lgkmcnt(0)
	v_mfma_f32_32x32x16_f16 v[32:47], v[108:111], v[224:227], v[32:47]
	v_cvt_pk_f16_f32 v227, v82, v83
	v_cvt_pk_f16_f32 v226, v84, v85
	v_cvt_pk_f16_f32 v225, v81, v86
	v_cvt_pk_f16_f32 v224, v80, v87
	v_fma_f32 v64, v93, s28, -v115
	v_exp_f32_e32 v98, v78
	v_fma_f32 v78, v95, s28, -v115
	v_mfma_f32_32x32x16_f16 v[16:31], v[210:213], v[224:227], v[16:31]
	ds_read_b128 v[210:213], v223 offset:8192
	v_exp_f32_e32 v78, v78
	v_exp_f32_e32 v64, v64
	v_exp_f32_e32 v72, v72
	v_exp_f32_e32 v90, v97
	v_cvt_pk_f16_f32 v95, v98, v78
	v_cvt_pk_f16_f32 v94, v68, v64
	v_mfma_f32_32x32x16_f16 v[0:15], v[108:111], v[224:227], v[0:15]
	ds_read_b128 v[108:111], v223 offset:12288
	v_cvt_pk_f16_f32 v227, v99, v79
	v_cvt_pk_f16_f32 v226, v69, v65
	v_cvt_pk_f16_f32 v225, v207, v73
	v_cvt_pk_f16_f32 v224, v205, v206
	v_cvt_pk_f16_f32 v93, v89, v72
	v_cvt_pk_f16_f32 v92, v88, v90
	s_waitcnt lgkmcnt(1)
	v_mfma_f32_32x32x16_f16 v[48:63], v[210:213], v[224:227], v[48:63]
	s_waitcnt lgkmcnt(0)
	v_mfma_f32_32x32x16_f16 v[32:47], v[108:111], v[224:227], v[32:47]
	v_mfma_f32_32x32x16_f16 v[16:31], v[210:213], v[92:95], v[16:31]
	v_mfma_f32_32x32x16_f16 v[0:15], v[108:111], v[92:95], v[0:15]
	s_cbranch_vccnz .LBB0_79
	s_add_i32 s24, s44, 0x4000
	s_mov_b64 s[2:3], 0

; DI void attn_task(const Params& P, int set, int b, int kvh, int qt, char* smem) {
;     ...
;   for (int kt = 0; kt < ntile; ++kt) {
;     if (kt + 1 < ntile) {
;       kreg = *(const half8*)(kg + (size_t)((kt + 1) * 64 + srow) * 64 + sch * 8);
;       vreg = *(const half8*)(vg + (size_t)srow * SKV + (kt + 1) * 64 + sch * 8);
;     }
;     const char* s = smem + (kt & 1) * 16384;
;     ...
;       float ps = 0.f;
; #pragma unroll
;       for (int v = 0; v < 16; ++v) {
;         sc[qi][0][v] = __builtin_amdgcn_exp2f(sc[qi][0][v] * cscale - m_new); ps += sc[qi][0][v];
;         sc[qi][1][v] = __builtin_amdgcn_exp2f(sc[qi][1][v] * cscale - m_new); ps += sc[qi][1][v];
;       }
;       l_run[qi] = l_run[qi] * alpha + ps;
; #pragma unroll
;       for (int v = 0; v < 16; ++v) { o[qi][0][v] *= alpha; o[qi][1][v] *= alpha; }
.LBB0_84:
	v_add_f32_e32 v91, v190, v189
	v_add_f32_e32 v80, v80, v119
	v_add_f32_e32 v91, v191, v91
	v_add_f32_e32 v80, v120, v80
	v_add_f32_e32 v91, v192, v91
	v_add_f32_e32 v80, v87, v80
	v_add_f32_e32 v91, v193, v91
	v_add_f32_e32 v80, v121, v80
	v_add_f32_e32 v91, v194, v91
	v_add_f32_e32 v80, v81, v80
	v_add_f32_e32 v91, v195, v91
	v_add_f32_e32 v80, v122, v80
	v_add_f32_e32 v91, v196, v91
	v_add_f32_e32 v80, v86, v80
	v_add_f32_e32 v91, v197, v91
	v_add_f32_e32 v80, v100, v80
	v_add_f32_e32 v91, v198, v91
	v_add_f32_e32 v80, v84, v80
	v_add_f32_e32 v91, v199, v91
	v_add_f32_e32 v80, v101, v80
	v_add_f32_e32 v91, v200, v91
	v_add_f32_e32 v80, v85, v80
	v_add_f32_e32 v91, v201, v91
	v_add_f32_e32 v80, v102, v80
	v_add_f32_e32 v91, v202, v91
	v_add_f32_e32 v80, v82, v80
	v_add_f32_e32 v91, v203, v91
	v_add_f32_e32 v80, v103, v80
	v_add_f32_e32 v91, v204, v91
	v_add_f32_e32 v80, v83, v80
	v_add_f32_e32 v91, v116, v91
	v_add_f32_e32 v80, v104, v80
	v_add_f32_e32 v91, v205, v91
	v_add_f32_e32 v80, v88, v80
	v_add_f32_e32 v91, v117, v91
	v_add_f32_e32 v80, v106, v80
	v_add_f32_e32 v91, v206, v91
	v_add_f32_e32 v80, v90, v80
	v_add_f32_e32 v91, v118, v91
	v_add_f32_e32 v80, v105, v80
	v_add_f32_e32 v91, v207, v91
	v_add_f32_e32 v90, v89, v80
	v_pk_add_f32 v[80:81], v[112:113], v[90:91]
	v_mov_b32_e32 v97, v114
	v_pk_add_f32 v[72:73], v[72:73], v[80:81]
	s_add_i32 s43, s43, 1
	v_pk_add_f32 v[70:71], v[70:71], v[72:73]
	s_mov_b64 s[2:3], 0x2000
	v_pk_add_f32 v[68:69], v[68:69], v[70:71]
	v_lshl_add_u64 v[176:177], v[176:177], 0, s[2:3]
	v_pk_add_f32 v[66:67], v[66:67], v[68:69]
	v_lshl_add_u64 v[178:179], v[178:179], 0, s[22:23]
	v_pk_add_f32 v[64:65], v[64:65], v[66:67]
	s_cmp_lg_u32 s43, 36
	v_pk_add_f32 v[64:65], v[76:77], v[64:65]
	s_mov_b32 s44, s24
	v_pk_add_f32 v[64:65], v[98:99], v[64:65]
	v_mov_b32_e32 v224, v115
	v_pk_add_f32 v[64:65], v[74:75], v[64:65]
	v_mov_b32_e32 v80, v128
	v_pk_add_f32 v[64:65], v[78:79], v[64:65]
	s_waitcnt lgkmcnt(0)
	v_pk_fma_f32 v[168:169], v[168:169], v[96:97], v[64:65]
	s_barrier
	s_cbranch_scc0 .LBB0_69
